# GLA scan pass 0: output-row stores split between the two k-half wave pairs (each publishes 8 partial rows and stores 8) instead of one pair storing all 16
# speedup vs baseline: 1.1102x; 1.0031x over previous
.LBB0_1057:
	ds_read_b128 v[108:111], v172 offset:32768
	ds_read_b128 v[112:115], v172 offset:32800
	ds_read_b128 v[116:119], v172 offset:32832
	ds_read_b128 v[128:131], v172 offset:32864
	ds_read_b128 v[120:123], v172 offset:32896
	ds_read_b128 v[124:127], v172 offset:32928
	ds_read_b128 v[132:135], v172 offset:32960
	ds_read_b128 v[136:139], v172 offset:32992
	s_waitcnt lgkmcnt(4)
	v_pk_mul_f32 v[46:47], v[14:15], v[130:131]
	v_pk_mul_f32 v[42:43], v[10:11], v[118:119]
	v_pk_mul_f32 v[38:39], v[6:7], v[114:115]
	v_pk_mul_f32 v[34:35], v[2:3], v[110:111]
	v_pk_mul_f32 v[44:45], v[12:13], v[128:129]
	v_pk_mul_f32 v[40:41], v[8:9], v[116:117]
	v_pk_mul_f32 v[36:37], v[4:5], v[112:113]
	v_pk_mul_f32 v[32:33], v[0:1], v[108:109]
	s_waitcnt lgkmcnt(0)
	v_pk_mul_f32 v[62:63], v[30:31], v[138:139]
	v_pk_mul_f32 v[58:59], v[26:27], v[134:135]
	v_pk_mul_f32 v[54:55], v[22:23], v[126:127]
	v_pk_mul_f32 v[50:51], v[18:19], v[122:123]
	v_pk_mul_f32 v[60:61], v[28:29], v[136:137]
	v_pk_mul_f32 v[56:57], v[24:25], v[132:133]
	v_pk_mul_f32 v[52:53], v[20:21], v[124:125]
	s_and_b64 vcc, exec, s[76:77]
	v_pk_mul_f32 v[48:49], v[16:17], v[120:121]
	s_cbranch_vccnz .LBB0_1061
	v_pk_mul_f32 v[22:23], v[28:29], v[136:137]
	v_pk_mul_f32 v[28:29], v[8:9], v[116:117]
	v_pk_mul_f32 v[2:3], v[4:5], v[112:113]
	v_pk_mul_f32 v[0:1], v[0:1], v[108:109]
	ds_read_b128 v[200:203], v236 offset:8704
	ds_read_b128 v[204:207], v237
	ds_read_b128 v[208:211], v237 offset:32
	ds_read_b128 v[212:215], v238 offset:8704
	ds_read_b128 v[216:219], v239 offset:8704
	ds_read_b128 v[194:197], v237 offset:64
	v_pk_mul_f32 v[26:27], v[12:13], v[128:129]
	v_pk_mul_f32 v[30:31], v[16:17], v[120:121]
	s_waitcnt lgkmcnt(4)
	v_mfma_f32_32x32x16_bf16 v[4:19], v[200:203], v[204:207], 0
	ds_read_b128 v[200:203], v240 offset:8704
	ds_read_b128 v[204:207], v237 offset:96
	v_readlane_b32 s16, v254, 63
	v_readlane_b32 s17, v255, 0
	v_cvt_pk_bf16_f32 v0, v0, v1
	v_cvt_pk_bf16_f32 v1, v34, v35
	v_cvt_pk_bf16_f32 v2, v2, v3
	v_cvt_pk_bf16_f32 v3, v38, v39
	v_pk_mul_f32 v[24:25], v[24:25], v[132:133]
	s_waitcnt lgkmcnt(4)
	v_mfma_f32_32x32x16_bf16 v[4:19], v[212:215], v[208:211], v[4:19]
	ds_read_b128 v[208:211], v241 offset:8704
	ds_read_b128 v[212:215], v237 offset:128
	v_mul_f32_e64 v20, v20, v124
	v_mul_f32_e64 v21, v21, v125
	v_cvt_pk_bf16_f32 v116, v30, v31
	v_cvt_pk_bf16_f32 v117, v50, v51
	v_cvt_pk_bf16_f32 v118, v20, v21
	v_cvt_pk_bf16_f32 v119, v54, v55
	v_cvt_pk_bf16_f32 v28, v28, v29
	s_waitcnt lgkmcnt(4)
	v_mfma_f32_32x32x16_bf16 v[4:19], v[216:219], v[194:197], v[4:19]
	ds_read_b128 v[216:219], v242 offset:8704
	ds_read_b128 v[194:197], v237 offset:160
	v_cvt_pk_bf16_f32 v29, v42, v43
	v_cvt_pk_bf16_f32 v30, v26, v27
	v_cvt_pk_bf16_f32 v31, v46, v47
	v_cvt_pk_bf16_f32 v20, v24, v25
	v_cvt_pk_bf16_f32 v21, v58, v59
	v_cvt_pk_bf16_f32 v22, v22, v23
	s_waitcnt lgkmcnt(4)
	v_mfma_f32_32x32x16_bf16 v[4:19], v[200:203], v[204:207], v[4:19]
	ds_read_b128 v[200:203], v243 offset:8704
	ds_read_b128 v[204:207], v237 offset:192
	v_cvt_pk_bf16_f32 v23, v62, v63
	s_waitcnt lgkmcnt(4)
	v_mfma_f32_32x32x16_bf16 v[4:19], v[208:211], v[212:215], v[4:19]
	ds_read_b128 v[208:211], v244 offset:8704
	ds_read_b128 v[212:215], v237 offset:224
	s_waitcnt lgkmcnt(4)
	v_mfma_f32_32x32x16_bf16 v[4:19], v[216:219], v[194:197], v[4:19]
	s_waitcnt lgkmcnt(2)
	v_mfma_f32_32x32x16_bf16 v[4:19], v[200:203], v[204:207], v[4:19]
	s_waitcnt lgkmcnt(0)
	v_mfma_f32_32x32x16_bf16 v[4:19], v[208:211], v[212:215], v[4:19]
	s_nop 11
	v_cndmask_b32_e64 v64, v4, 0, s[16:17]
	v_readlane_b32 s16, v255, 1
	v_readlane_b32 s17, v255, 2
	v_cndmask_b32_e64 v64, v64, v4, s[40:41]
	v_cndmask_b32_e64 v120, 0, v5, s[40:41]
	v_cndmask_b32_e64 v121, v6, 0, s[16:17]
	v_readlane_b32 s16, v255, 3
	v_readlane_b32 s17, v255, 4
	v_cndmask_b32_e64 v123, v8, 0, s[48:49]
	v_cndmask_b32_e64 v124, v9, 0, s[52:53]
	v_cndmask_b32_e64 v122, v7, 0, s[16:17]
	v_readlane_b32 s16, v255, 5
	ds_read2_b64 v[4:7], v175 offset1:2
	ds_read2_b64 v[108:111], v175 offset0:4 offset1:6
	v_readlane_b32 s17, v255, 6
	ds_read2_b64 v[112:115], v175 offset0:8 offset1:10
	v_cndmask_b32_e64 v125, v10, 0, s[44:45]
	v_cndmask_b32_e64 v128, v13, 0, s[16:17]
	v_readlane_b32 s16, v255, 7
	v_readlane_b32 s17, v255, 8
	v_cndmask_b32_e64 v126, v11, 0, s[36:37]
	v_cndmask_b32_e64 v127, v12, 0, s[42:43]
	v_cndmask_b32_e64 v129, v14, 0, s[16:17]
	v_cndmask_b32_e64 v130, v15, 0, s[60:61]
	v_cndmask_b32_e64 v131, v16, 0, s[62:63]
	v_cndmask_b32_e64 v132, v17, 0, s[64:65]
	s_waitcnt lgkmcnt(2)
	v_mfma_f32_32x32x16_bf16 v[2:17], v[4:7], v[0:3], 0
	v_cndmask_b32_e64 v18, v18, 0, s[66:67]
	v_cndmask_b32_e64 v0, v19, 0, s[68:69]
	v_cvt_pk_bf16_f32 v1, v64, v120
	v_cvt_pk_bf16_f32 v19, v121, v122
	v_cvt_pk_bf16_f32 v24, v131, v132
	v_cvt_pk_bf16_f32 v0, v18, v0
	s_waitcnt lgkmcnt(0)
	v_mfma_f32_32x32x16_bf16 v[2:17], v[112:115], v[116:119], v[2:17]
	v_mfma_f32_32x32x16_bf16 v[2:17], v[108:111], v[28:31], v[2:17]
	ds_read2_b64 v[26:29], v175 offset0:12 offset1:14
	s_waitcnt lgkmcnt(0)
	v_mfma_f32_32x32x16_bf16 v[2:17], v[26:29], v[20:23], v[2:17]
	v_cvt_pk_bf16_f32 v20, v123, v124
	v_cvt_pk_bf16_f32 v21, v125, v126
	v_cvt_pk_bf16_f32 v22, v127, v128
	v_cvt_pk_bf16_f32 v23, v129, v130
	v_cndmask_b32_e64 v21, v0, v21, s[70:71]
	v_cndmask_b32_e64 v20, v24, v20, s[70:71]
	v_cndmask_b32_e64 v19, v23, v19, s[70:71]
	v_cndmask_b32_e64 v18, v22, v1, s[70:71]
	ds_read_b64_tr_b16 v[22:23], v156
	ds_read_b64_tr_b16 v[24:25], v157
	s_waitcnt lgkmcnt(0)
	s_nop 1
	v_mfma_f32_32x32x16_bf16 v[2:17], v[18:21], v[22:25], v[2:17]
	s_mov_b64 s[20:21], exec
	s_cmp_lg_u64 s[72:73], 0
	s_cbranch_scc0 .Lsow0_k0
	v_add_u32_e32 v0, 0x8000, v231
	s_nop 8
	ds_write2_b32 v0, v2, v3 offset0:128 offset1:160
	ds_write2_b32 v0, v4, v5 offset0:192 offset1:224
	v_add_u32_e32 v0, 0x8400, v231
	ds_write2_b32 v0, v6, v7 offset0:128 offset1:160
	ds_write2_b32 v0, v8, v9 offset0:192 offset1:224
	s_branch .LBB0_1060
.Lsow0_k0:
	v_add_u32_e32 v0, 0x8800, v231
	s_nop 8
	ds_write2_b32 v0, v10, v11 offset0:128 offset1:160
	ds_write2_b32 v0, v12, v13 offset0:192 offset1:224
	v_add_u32_e32 v0, 0x8c00, v231
	ds_write2_b32 v0, v14, v15 offset0:128 offset1:160
	ds_write2_b32 v0, v16, v17 offset0:192 offset1:224

.LBB0_1061:
	ds_read_b64_tr_b16 v[116:117], v158
	ds_read_b64_tr_b16 v[118:119], v159
	ds_read_b64_tr_b16 v[112:113], v160
	ds_read_b64_tr_b16 v[114:115], v161
	ds_read_b64_tr_b16 v[108:109], v162
	ds_read_b64_tr_b16 v[110:111], v163
	ds_read_b64_tr_b16 v[26:27], v164
	ds_read_b64_tr_b16 v[28:29], v165
	ds_read_b64_tr_b16 v[22:23], v152
	ds_read_b64_tr_b16 v[24:25], v153
	ds_read_b64_tr_b16 v[18:19], v154
	ds_read_b64_tr_b16 v[20:21], v155
	s_waitcnt lgkmcnt(0)
	v_add_u32_e32 v251, 0x8000, v232
	v_mfma_f32_32x32x16_bf16 v[32:47], v[116:119], v[22:25], v[32:47]
	v_add_u32_e32 v250, 0x8400, v232
	v_add_u32_e32 v249, 0x8800, v232
	v_add_u32_e32 v64, 0x8c00, v232
	s_waitcnt lgkmcnt(0)
	s_barrier
	v_mfma_f32_32x32x16_bf16 v[48:63], v[108:111], v[22:25], v[48:63]
	v_mfma_f32_32x32x16_bf16 v[32:47], v[112:115], v[18:21], v[32:47]
	v_mfma_f32_32x32x16_bf16 v[48:63], v[26:29], v[18:21], v[48:63]
	s_mov_b64 vcc, exec
	s_cmp_lg_u64 s[8:9], 0
	s_cbranch_scc1 .Lsos0_k0
	s_cmp_lg_u64 s[72:73], 0
	s_cbranch_scc0 .LBB0_1063
	s_cmp_lg_u64 s[76:77], 0
	s_cbranch_scc1 .LBB0_1063
	s_sub_i32 s20, s95, 64
	s_and_b64 s[18:19], s[74:75], exec
	s_cselect_b32 s18, s20, s34
	s_ashr_i32 s19, s18, 31
	s_add_u32 s20, s18, s97
	s_addc_u32 s21, s19, s84
	v_add_u32_e32 v194, 0x8800, v231
	ds_read2_b32 v[208:209], v194 offset0:128 offset1:160
	ds_read2_b32 v[210:211], v194 offset0:192 offset1:224
	v_add_u32_e32 v195, 0x8c00, v231
	ds_read2_b32 v[212:213], v195 offset0:128 offset1:160
	ds_read2_b32 v[214:215], v195 offset0:192 offset1:224
	s_waitcnt lgkmcnt(3)
	v_add_f32_e32 v218, v10, v208
	s_add_u32 s18, s20, s4
	s_addc_u32 s19, s21, s6
	s_lshl_b64 s[18:19], s[18:19], 11
	v_cvt_pk_bf16_f32 v218, v218, v218
	v_lshl_add_u64 v[216:217], v[146:147], 0, s[18:19]
	global_store_short v[216:217], v218, off
	v_add_f32_e32 v219, v11, v209
	s_add_u32 s18, s20, s7
	s_addc_u32 s19, s21, s39
	s_lshl_b64 s[18:19], s[18:19], 11
	v_cvt_pk_bf16_f32 v219, v219, v219
	v_lshl_add_u64 v[216:217], v[146:147], 0, s[18:19]
	global_store_short v[216:217], v219, off
	s_waitcnt lgkmcnt(2)
	v_add_f32_e32 v218, v12, v210
	s_add_u32 s18, s20, s23
	s_addc_u32 s19, s21, s13
	s_lshl_b64 s[18:19], s[18:19], 11
	v_cvt_pk_bf16_f32 v218, v218, v218
	v_lshl_add_u64 v[216:217], v[146:147], 0, s[18:19]
	global_store_short v[216:217], v218, off
	v_add_f32_e32 v219, v13, v211
	s_add_u32 s18, s20, s11
	s_addc_u32 s19, s21, s82
	s_lshl_b64 s[18:19], s[18:19], 11
	v_cvt_pk_bf16_f32 v219, v219, v219
	v_lshl_add_u64 v[216:217], v[146:147], 0, s[18:19]
	global_store_short v[216:217], v219, off
	s_waitcnt lgkmcnt(1)
	v_add_f32_e32 v218, v14, v212
	s_add_u32 s18, s20, s83
	s_addc_u32 s19, s21, s86
	s_lshl_b64 s[18:19], s[18:19], 11
	v_cvt_pk_bf16_f32 v218, v218, v218
	v_lshl_add_u64 v[216:217], v[146:147], 0, s[18:19]
	global_store_short v[216:217], v218, off
	v_add_f32_e32 v219, v15, v213
	s_add_u32 s18, s20, s87
	s_addc_u32 s19, s21, s90
	s_lshl_b64 s[18:19], s[18:19], 11
	v_cvt_pk_bf16_f32 v219, v219, v219
	v_lshl_add_u64 v[216:217], v[146:147], 0, s[18:19]
	global_store_short v[216:217], v219, off
	s_waitcnt lgkmcnt(0)
	v_add_f32_e32 v218, v16, v214
	s_add_u32 s18, s20, s91
	s_addc_u32 s19, s21, s92
	s_lshl_b64 s[18:19], s[18:19], 11
	v_cvt_pk_bf16_f32 v218, v218, v218
	v_lshl_add_u64 v[216:217], v[146:147], 0, s[18:19]
	global_store_short v[216:217], v218, off
	v_add_f32_e32 v219, v17, v215
	s_add_u32 s18, s20, s93
	s_addc_u32 s19, s21, s94
	s_lshl_b64 s[18:19], s[18:19], 11
	v_cvt_pk_bf16_f32 v219, v219, v219
	v_lshl_add_u64 v[216:217], v[146:147], 0, s[18:19]
	global_store_short v[216:217], v219, off
	s_branch .LBB0_1063
.Lsos0_k0:
	s_sub_i32 s20, s95, 64
	s_and_b64 s[18:19], s[74:75], exec
	s_cselect_b32 s18, s20, s34
	s_ashr_i32 s19, s18, 31
	s_add_u32 s20, s18, s97
	s_addc_u32 s21, s19, s84
	ds_read2_b32 v[200:201], v251 offset0:128 offset1:160
	ds_read2_b32 v[202:203], v251 offset0:192 offset1:224
	ds_read2_b32 v[204:205], v250 offset0:128 offset1:160
	ds_read2_b32 v[206:207], v250 offset0:192 offset1:224
	s_waitcnt lgkmcnt(3)
	v_add_f32_e32 v218, v2, v200
	s_lshl_b64 s[18:19], s[20:21], 11
	v_cvt_pk_bf16_f32 v218, v218, v218
	v_lshl_add_u64 v[216:217], v[146:147], 0, s[18:19]
	global_store_short v[216:217], v218, off
	v_add_f32_e32 v219, v3, v201
	s_add_u32 s18, s20, s14
	s_addc_u32 s19, s21, s12
	s_lshl_b64 s[18:19], s[18:19], 11
	v_cvt_pk_bf16_f32 v219, v219, v219
	v_lshl_add_u64 v[216:217], v[146:147], 0, s[18:19]
	global_store_short v[216:217], v219, off
	s_waitcnt lgkmcnt(2)
	v_add_f32_e32 v218, v4, v202
	s_add_u32 s18, s20, s15
	s_addc_u32 s19, s21, s26
	s_lshl_b64 s[18:19], s[18:19], 11
	v_cvt_pk_bf16_f32 v218, v218, v218
	v_lshl_add_u64 v[216:217], v[146:147], 0, s[18:19]
	global_store_short v[216:217], v218, off
	v_add_f32_e32 v219, v5, v203
	s_add_u32 s18, s20, s38
	s_addc_u32 s19, s21, s2
	s_lshl_b64 s[18:19], s[18:19], 11
	v_cvt_pk_bf16_f32 v219, v219, v219
	v_lshl_add_u64 v[216:217], v[146:147], 0, s[18:19]
	global_store_short v[216:217], v219, off
	s_waitcnt lgkmcnt(1)
	v_add_f32_e32 v218, v6, v204
	s_add_u32 s18, s20, s3
	s_addc_u32 s19, s21, s5
	s_lshl_b64 s[18:19], s[18:19], 11
	v_cvt_pk_bf16_f32 v218, v218, v218
	v_lshl_add_u64 v[216:217], v[146:147], 0, s[18:19]
	global_store_short v[216:217], v218, off
	v_add_f32_e32 v219, v7, v205
	s_add_u32 s18, s20, s79
	s_addc_u32 s19, s21, s81
	s_lshl_b64 s[18:19], s[18:19], 11
	v_cvt_pk_bf16_f32 v219, v219, v219
	v_lshl_add_u64 v[216:217], v[146:147], 0, s[18:19]
	global_store_short v[216:217], v219, off
	s_waitcnt lgkmcnt(0)
	v_add_f32_e32 v218, v8, v206
	s_add_u32 s18, s20, s27
	s_addc_u32 s19, s21, s22
	s_lshl_b64 s[18:19], s[18:19], 11
	v_cvt_pk_bf16_f32 v218, v218, v218
	v_lshl_add_u64 v[216:217], v[146:147], 0, s[18:19]
	global_store_short v[216:217], v218, off
	v_add_f32_e32 v219, v9, v207
	s_add_u32 s18, s20, s33
	s_addc_u32 s19, s21, s29
	s_lshl_b64 s[18:19], s[18:19], 11
	v_cvt_pk_bf16_f32 v219, v219, v219
	v_lshl_add_u64 v[216:217], v[146:147], 0, s[18:19]
	global_store_short v[216:217], v219, off
	s_branch .LBB0_1063

.LBB0_1073:
	ds_read_b128 v[108:111], v172 offset:32768
	ds_read_b128 v[112:115], v172 offset:32800
	ds_read_b128 v[116:119], v172 offset:32832
	ds_read_b128 v[128:131], v172 offset:32864
	ds_read_b128 v[120:123], v172 offset:32896
	ds_read_b128 v[124:127], v172 offset:32928
	ds_read_b128 v[132:135], v172 offset:32960
	ds_read_b128 v[136:139], v172 offset:32992
	s_waitcnt lgkmcnt(4)
	v_pk_mul_f32 v[14:15], v[46:47], v[130:131]
	v_pk_mul_f32 v[10:11], v[42:43], v[118:119]
	v_pk_mul_f32 v[6:7], v[38:39], v[114:115]
	v_pk_mul_f32 v[2:3], v[34:35], v[110:111]
	v_pk_mul_f32 v[12:13], v[44:45], v[128:129]
	v_pk_mul_f32 v[8:9], v[40:41], v[116:117]
	v_pk_mul_f32 v[4:5], v[36:37], v[112:113]
	v_pk_mul_f32 v[0:1], v[32:33], v[108:109]
	s_waitcnt lgkmcnt(0)
	v_pk_mul_f32 v[30:31], v[62:63], v[138:139]
	v_pk_mul_f32 v[26:27], v[58:59], v[134:135]
	v_pk_mul_f32 v[22:23], v[54:55], v[126:127]
	v_pk_mul_f32 v[18:19], v[50:51], v[122:123]
	v_pk_mul_f32 v[28:29], v[60:61], v[136:137]
	v_pk_mul_f32 v[24:25], v[56:57], v[132:133]
	v_pk_mul_f32 v[20:21], v[52:53], v[124:125]
	s_and_b64 vcc, exec, s[76:77]
	v_pk_mul_f32 v[16:17], v[48:49], v[120:121]
	s_cbranch_vccnz .LBB0_1077
	v_pk_mul_f32 v[54:55], v[60:61], v[136:137]
	v_pk_mul_f32 v[60:61], v[40:41], v[116:117]
	v_pk_mul_f32 v[34:35], v[36:37], v[112:113]
	v_pk_mul_f32 v[32:33], v[32:33], v[108:109]
	ds_read_b128 v[200:203], v236 offset:8704
	ds_read_b128 v[204:207], v237
	ds_read_b128 v[208:211], v237 offset:32
	ds_read_b128 v[212:215], v238 offset:8704
	ds_read_b128 v[216:219], v239 offset:8704
	ds_read_b128 v[194:197], v237 offset:64
	v_pk_mul_f32 v[58:59], v[44:45], v[128:129]
	v_pk_mul_f32 v[62:63], v[48:49], v[120:121]
	s_waitcnt lgkmcnt(4)
	v_mfma_f32_32x32x16_bf16 v[36:51], v[200:203], v[204:207], 0
	ds_read_b128 v[200:203], v240 offset:8704
	ds_read_b128 v[204:207], v237 offset:96
	v_readlane_b32 s16, v254, 63
	v_readlane_b32 s17, v255, 0
	v_cvt_pk_bf16_f32 v32, v32, v33
	v_cvt_pk_bf16_f32 v33, v2, v3
	v_cvt_pk_bf16_f32 v34, v34, v35
	v_cvt_pk_bf16_f32 v35, v6, v7
	v_pk_mul_f32 v[56:57], v[56:57], v[132:133]
	s_waitcnt lgkmcnt(4)
	v_mfma_f32_32x32x16_bf16 v[36:51], v[212:215], v[208:211], v[36:51]
	ds_read_b128 v[208:211], v241 offset:8704
	ds_read_b128 v[212:215], v237 offset:128
	v_mul_f32_e64 v52, v52, v124
	v_mul_f32_e64 v53, v53, v125
	v_cvt_pk_bf16_f32 v116, v62, v63
	v_cvt_pk_bf16_f32 v117, v18, v19
	v_cvt_pk_bf16_f32 v118, v52, v53
	v_cvt_pk_bf16_f32 v119, v22, v23
	v_cvt_pk_bf16_f32 v60, v60, v61
	s_waitcnt lgkmcnt(4)
	v_mfma_f32_32x32x16_bf16 v[36:51], v[216:219], v[194:197], v[36:51]
	ds_read_b128 v[216:219], v242 offset:8704
	ds_read_b128 v[194:197], v237 offset:160
	v_cvt_pk_bf16_f32 v61, v10, v11
	v_cvt_pk_bf16_f32 v62, v58, v59
	v_cvt_pk_bf16_f32 v63, v14, v15
	v_cvt_pk_bf16_f32 v52, v56, v57
	v_cvt_pk_bf16_f32 v53, v26, v27
	v_cvt_pk_bf16_f32 v54, v54, v55
	s_waitcnt lgkmcnt(4)
	v_mfma_f32_32x32x16_bf16 v[36:51], v[200:203], v[204:207], v[36:51]
	ds_read_b128 v[200:203], v243 offset:8704
	ds_read_b128 v[204:207], v237 offset:192
	v_cvt_pk_bf16_f32 v55, v30, v31
	s_waitcnt lgkmcnt(4)
	v_mfma_f32_32x32x16_bf16 v[36:51], v[208:211], v[212:215], v[36:51]
	ds_read_b128 v[208:211], v244 offset:8704
	ds_read_b128 v[212:215], v237 offset:224
	s_waitcnt lgkmcnt(4)
	v_mfma_f32_32x32x16_bf16 v[36:51], v[216:219], v[194:197], v[36:51]
	s_waitcnt lgkmcnt(2)
	v_mfma_f32_32x32x16_bf16 v[36:51], v[200:203], v[204:207], v[36:51]
	s_waitcnt lgkmcnt(0)
	v_mfma_f32_32x32x16_bf16 v[36:51], v[208:211], v[212:215], v[36:51]
	s_nop 11
	v_cndmask_b32_e64 v108, v36, 0, s[16:17]
	v_readlane_b32 s16, v255, 1
	v_readlane_b32 s17, v255, 2
	v_cndmask_b32_e64 v120, v108, v36, s[40:41]
	v_cndmask_b32_e64 v121, 0, v37, s[40:41]
	v_cndmask_b32_e64 v122, v38, 0, s[16:17]
	v_readlane_b32 s16, v255, 3
	v_readlane_b32 s17, v255, 4
	v_cndmask_b32_e64 v124, v40, 0, s[48:49]
	v_cndmask_b32_e64 v125, v41, 0, s[52:53]
	v_cndmask_b32_e64 v123, v39, 0, s[16:17]
	v_readlane_b32 s16, v255, 5
	ds_read2_b64 v[36:39], v175 offset1:2
	ds_read2_b64 v[108:111], v175 offset0:4 offset1:6
	v_readlane_b32 s17, v255, 6
	ds_read2_b64 v[112:115], v175 offset0:8 offset1:10
	v_cndmask_b32_e64 v126, v42, 0, s[44:45]
	v_cndmask_b32_e64 v129, v45, 0, s[16:17]
	v_readlane_b32 s16, v255, 7
	v_readlane_b32 s17, v255, 8
	v_cndmask_b32_e64 v127, v43, 0, s[36:37]
	v_cndmask_b32_e64 v128, v44, 0, s[42:43]
	v_cndmask_b32_e64 v130, v46, 0, s[16:17]
	v_cndmask_b32_e64 v131, v47, 0, s[60:61]
	v_cndmask_b32_e64 v132, v48, 0, s[62:63]
	v_cndmask_b32_e64 v133, v49, 0, s[64:65]
	s_waitcnt lgkmcnt(2)
	v_mfma_f32_32x32x16_bf16 v[34:49], v[36:39], v[32:35], 0
	v_cndmask_b32_e64 v50, v50, 0, s[66:67]
	v_cndmask_b32_e64 v32, v51, 0, s[68:69]
	v_cvt_pk_bf16_f32 v33, v120, v121
	v_cvt_pk_bf16_f32 v51, v122, v123
	v_cvt_pk_bf16_f32 v56, v132, v133
	v_cvt_pk_bf16_f32 v32, v50, v32
	s_waitcnt lgkmcnt(0)
	v_mfma_f32_32x32x16_bf16 v[34:49], v[112:115], v[116:119], v[34:49]
	v_mfma_f32_32x32x16_bf16 v[34:49], v[108:111], v[60:63], v[34:49]
	ds_read2_b64 v[58:61], v175 offset0:12 offset1:14
	s_waitcnt lgkmcnt(0)
	v_mfma_f32_32x32x16_bf16 v[34:49], v[58:61], v[52:55], v[34:49]
	v_cvt_pk_bf16_f32 v52, v124, v125
	v_cvt_pk_bf16_f32 v53, v126, v127
	v_cvt_pk_bf16_f32 v54, v128, v129
	v_cvt_pk_bf16_f32 v55, v130, v131
	v_cndmask_b32_e64 v53, v32, v53, s[70:71]
	v_cndmask_b32_e64 v52, v56, v52, s[70:71]
	v_cndmask_b32_e64 v51, v55, v51, s[70:71]
	v_cndmask_b32_e64 v50, v54, v33, s[70:71]
	ds_read_b64_tr_b16 v[54:55], v156
	ds_read_b64_tr_b16 v[56:57], v157
	s_waitcnt lgkmcnt(0)
	s_nop 1
	v_mfma_f32_32x32x16_bf16 v[34:49], v[50:53], v[54:57], v[34:49]
	s_mov_b64 s[20:21], exec
	s_cmp_lg_u64 s[72:73], 0
	s_cbranch_scc0 .Lsow1_k0
	v_add_u32_e32 v32, 0x8000, v231
	s_nop 8
	ds_write2_b32 v32, v34, v35 offset0:128 offset1:160
	ds_write2_b32 v32, v36, v37 offset0:192 offset1:224
	v_add_u32_e32 v32, 0x8400, v231
	ds_write2_b32 v32, v38, v39 offset0:128 offset1:160
	ds_write2_b32 v32, v40, v41 offset0:192 offset1:224
	s_branch .LBB0_1076
.Lsow1_k0:
	v_add_u32_e32 v32, 0x8800, v231
	s_nop 8
	ds_write2_b32 v32, v42, v43 offset0:128 offset1:160
	ds_write2_b32 v32, v44, v45 offset0:192 offset1:224
	v_add_u32_e32 v32, 0x8c00, v231
	ds_write2_b32 v32, v46, v47 offset0:128 offset1:160
	ds_write2_b32 v32, v48, v49 offset0:192 offset1:224

.LBB0_1077:
	ds_read_b64_tr_b16 v[116:117], v158
	ds_read_b64_tr_b16 v[118:119], v159
	ds_read_b64_tr_b16 v[112:113], v160
	ds_read_b64_tr_b16 v[114:115], v161
	ds_read_b64_tr_b16 v[108:109], v162
	ds_read_b64_tr_b16 v[110:111], v163
	ds_read_b64_tr_b16 v[58:59], v164
	ds_read_b64_tr_b16 v[60:61], v165
	ds_read_b64_tr_b16 v[54:55], v152
	ds_read_b64_tr_b16 v[56:57], v153
	ds_read_b64_tr_b16 v[50:51], v154
	ds_read_b64_tr_b16 v[52:53], v155
	s_waitcnt lgkmcnt(0)
	s_waitcnt lgkmcnt(0)
	v_mfma_f32_32x32x16_bf16 v[0:15], v[116:119], v[54:57], v[0:15]
	s_barrier
	v_mfma_f32_32x32x16_bf16 v[16:31], v[108:111], v[54:57], v[16:31]
	v_mfma_f32_32x32x16_bf16 v[0:15], v[112:115], v[50:53], v[0:15]
	v_mfma_f32_32x32x16_bf16 v[16:31], v[58:61], v[50:53], v[16:31]
	s_mov_b64 s[24:25], exec
	s_cmp_lg_u64 s[8:9], 0
	s_cbranch_scc1 .Lsos1_k0
	s_cmp_lg_u64 s[72:73], 0
	s_cbranch_scc0 .LBB0_1046
	s_cmp_lg_u64 s[76:77], 0
	s_cbranch_scc1 .LBB0_1046
	s_and_b64 s[18:19], s[74:75], exec
	s_cselect_b32 s18, s95, s34
	s_sub_i32 s18, s18, 32
	s_ashr_i32 s19, s18, 31
	s_add_u32 s20, s18, s97
	s_addc_u32 s21, s19, s84
	v_add_u32_e32 v194, 0x8800, v231
	ds_read2_b32 v[208:209], v194 offset0:128 offset1:160
	ds_read2_b32 v[210:211], v194 offset0:192 offset1:224
	v_add_u32_e32 v195, 0x8c00, v231
	ds_read2_b32 v[212:213], v195 offset0:128 offset1:160
	ds_read2_b32 v[214:215], v195 offset0:192 offset1:224
	s_waitcnt lgkmcnt(3)
	v_add_f32_e32 v218, v42, v208
	s_add_u32 s18, s20, s4
	s_addc_u32 s19, s21, s6
	s_lshl_b64 s[18:19], s[18:19], 11
	v_cvt_pk_bf16_f32 v218, v218, v218
	v_lshl_add_u64 v[216:217], v[146:147], 0, s[18:19]
	global_store_short v[216:217], v218, off
	v_add_f32_e32 v219, v43, v209
	s_add_u32 s18, s20, s7
	s_addc_u32 s19, s21, s39
	s_lshl_b64 s[18:19], s[18:19], 11
	v_cvt_pk_bf16_f32 v219, v219, v219
	v_lshl_add_u64 v[216:217], v[146:147], 0, s[18:19]
	global_store_short v[216:217], v219, off
	s_waitcnt lgkmcnt(2)
	v_add_f32_e32 v218, v44, v210
	s_add_u32 s18, s20, s23
	s_addc_u32 s19, s21, s13
	s_lshl_b64 s[18:19], s[18:19], 11
	v_cvt_pk_bf16_f32 v218, v218, v218
	v_lshl_add_u64 v[216:217], v[146:147], 0, s[18:19]
	global_store_short v[216:217], v218, off
	v_add_f32_e32 v219, v45, v211
	s_add_u32 s18, s20, s11
	s_addc_u32 s19, s21, s82
	s_lshl_b64 s[18:19], s[18:19], 11
	v_cvt_pk_bf16_f32 v219, v219, v219
	v_lshl_add_u64 v[216:217], v[146:147], 0, s[18:19]
	global_store_short v[216:217], v219, off
	s_waitcnt lgkmcnt(1)
	v_add_f32_e32 v218, v46, v212
	s_add_u32 s18, s20, s83
	s_addc_u32 s19, s21, s86
	s_lshl_b64 s[18:19], s[18:19], 11
	v_cvt_pk_bf16_f32 v218, v218, v218
	v_lshl_add_u64 v[216:217], v[146:147], 0, s[18:19]
	global_store_short v[216:217], v218, off
	v_add_f32_e32 v219, v47, v213
	s_add_u32 s18, s20, s87
	s_addc_u32 s19, s21, s90
	s_lshl_b64 s[18:19], s[18:19], 11
	v_cvt_pk_bf16_f32 v219, v219, v219
	v_lshl_add_u64 v[216:217], v[146:147], 0, s[18:19]
	global_store_short v[216:217], v219, off
	s_waitcnt lgkmcnt(0)
	v_add_f32_e32 v218, v48, v214
	s_add_u32 s18, s20, s91
	s_addc_u32 s19, s21, s92
	s_lshl_b64 s[18:19], s[18:19], 11
	v_cvt_pk_bf16_f32 v218, v218, v218
	v_lshl_add_u64 v[216:217], v[146:147], 0, s[18:19]
	global_store_short v[216:217], v218, off
	v_add_f32_e32 v219, v49, v215
	s_add_u32 s18, s20, s93
	s_addc_u32 s19, s21, s94
	s_lshl_b64 s[18:19], s[18:19], 11
	v_cvt_pk_bf16_f32 v219, v219, v219
	v_lshl_add_u64 v[216:217], v[146:147], 0, s[18:19]
	global_store_short v[216:217], v219, off
	s_branch .LBB0_1046
.Lsos1_k0:
	s_and_b64 s[18:19], s[74:75], exec
	s_cselect_b32 s18, s95, s34
	s_sub_i32 s18, s18, 32
	s_ashr_i32 s19, s18, 31
	s_add_u32 s20, s18, s97
	s_addc_u32 s21, s19, s84
	ds_read2_b32 v[200:201], v251 offset0:128 offset1:160
	ds_read2_b32 v[202:203], v251 offset0:192 offset1:224
	ds_read2_b32 v[204:205], v250 offset0:128 offset1:160
	ds_read2_b32 v[206:207], v250 offset0:192 offset1:224
	s_waitcnt lgkmcnt(3)
	v_add_f32_e32 v218, v34, v200
	s_lshl_b64 s[18:19], s[20:21], 11
	v_cvt_pk_bf16_f32 v218, v218, v218
	v_lshl_add_u64 v[216:217], v[146:147], 0, s[18:19]
	global_store_short v[216:217], v218, off
	v_add_f32_e32 v219, v35, v201
	s_add_u32 s18, s20, s14
	s_addc_u32 s19, s21, s12
	s_lshl_b64 s[18:19], s[18:19], 11
	v_cvt_pk_bf16_f32 v219, v219, v219
	v_lshl_add_u64 v[216:217], v[146:147], 0, s[18:19]
	global_store_short v[216:217], v219, off
	s_waitcnt lgkmcnt(2)
	v_add_f32_e32 v218, v36, v202
	s_add_u32 s18, s20, s15
	s_addc_u32 s19, s21, s26
	s_lshl_b64 s[18:19], s[18:19], 11
	v_cvt_pk_bf16_f32 v218, v218, v218
	v_lshl_add_u64 v[216:217], v[146:147], 0, s[18:19]
	global_store_short v[216:217], v218, off
	v_add_f32_e32 v219, v37, v203
	s_add_u32 s18, s20, s38
	s_addc_u32 s19, s21, s2
	s_lshl_b64 s[18:19], s[18:19], 11
	v_cvt_pk_bf16_f32 v219, v219, v219
	v_lshl_add_u64 v[216:217], v[146:147], 0, s[18:19]
	global_store_short v[216:217], v219, off
	s_waitcnt lgkmcnt(1)
	v_add_f32_e32 v218, v38, v204
	s_add_u32 s18, s20, s3
	s_addc_u32 s19, s21, s5
	s_lshl_b64 s[18:19], s[18:19], 11
	v_cvt_pk_bf16_f32 v218, v218, v218
	v_lshl_add_u64 v[216:217], v[146:147], 0, s[18:19]
	global_store_short v[216:217], v218, off
	v_add_f32_e32 v219, v39, v205
	s_add_u32 s18, s20, s79
	s_addc_u32 s19, s21, s81
	s_lshl_b64 s[18:19], s[18:19], 11
	v_cvt_pk_bf16_f32 v219, v219, v219
	v_lshl_add_u64 v[216:217], v[146:147], 0, s[18:19]
	global_store_short v[216:217], v219, off
	s_waitcnt lgkmcnt(0)
	v_add_f32_e32 v218, v40, v206
	s_add_u32 s18, s20, s27
	s_addc_u32 s19, s21, s22
	s_lshl_b64 s[18:19], s[18:19], 11
	v_cvt_pk_bf16_f32 v218, v218, v218
	v_lshl_add_u64 v[216:217], v[146:147], 0, s[18:19]
	global_store_short v[216:217], v218, off
	v_add_f32_e32 v219, v41, v207
	s_add_u32 s18, s20, s33
	s_addc_u32 s19, s21, s29
	s_lshl_b64 s[18:19], s[18:19], 11
	v_cvt_pk_bf16_f32 v219, v219, v219
	v_lshl_add_u64 v[216:217], v[146:147], 0, s[18:19]
	global_store_short v[216:217], v219, off
	s_branch .LBB0_1046
